# phase-5 attention tiles dealt to worker waves in reverse order (carry workgroups get the short share), on top of the forward-substitution rewrite
# speedup vs baseline: 1.0203x; 1.0051x over previous
.LBB0_2470:
	v_mov_b32_e32 v2, v0
	v_readlane_b32 s2, v249, 3
	v_readfirstlane_b32 s1, v2
	s_ashr_i32 s0, s1, 6
	v_readlane_b32 s4, v249, 4
	s_add_i32 s2, s2, s0
	s_add_i32 s4, s4, s0
	s_cmp_gt_u32 s1, 63
	s_cselect_b32 s1, s4, -1
	v_readlane_b32 s4, v249, 1
	v_readlane_b32 s5, v249, 2
	s_and_b64 s[4:5], s[4:5], exec
	s_cselect_b32 s1, s1, s2
	s_cmp_lt_i32 s1, 0
	s_cbranch_scc1 .LBB0_2530
	v_readlane_b32 s2, v249, 0
	s_sub_i32 s2, s2, 1
	s_sub_i32 s1, s2, s1
	v_readlane_b32 s2, v253, 35
	s_add_i32 s1, s1, s2
	v_readlane_b32 s2, v253, 34
	s_cmp_ge_u32 s1, s2
	s_cbranch_scc1 .LBB0_2530
	v_and_b32_e32 v4, 63, v2
	v_or_b32_e32 v8, 0x80, v4
	s_mulk_i32 s0, 0x4100
	s_waitcnt lgkmcnt(0)
	v_bfe_u32 v3, v2, 5, 1
	v_or_b32_e32 v7, 64, v4
	v_lshrrev_b32_e32 v8, 3, v8
	s_add_i32 s0, s0, 0
	v_lshrrev_b32_e32 v7, 3, v7
	s_waitcnt vmcnt(6)
	v_lshlrev_b32_e32 v122, 7, v8
	v_mul_u32_u24_e32 v134, 0x90, v8
	v_lshrrev_b32_e32 v8, 2, v2
	v_lshlrev_b32_e32 v138, 2, v3
	v_and_b32_e32 v1, 31, v2
	s_waitcnt vmcnt(5)
	v_lshlrev_b32_e32 v114, 3, v3
	v_lshlrev_b32_e32 v120, 7, v7
	v_mul_u32_u24_e32 v127, 0x90, v7
	v_mov_b32_e32 v7, s0
	s_movk_i32 s2, 0x90
	v_lshlrev_b32_e32 v137, 4, v3
	v_and_or_b32 v3, v8, 3, v138
	v_readlane_b32 s4, v253, 20
	v_lshlrev_b32_e32 v5, 3, v4
	v_mad_u32_u24 v136, v1, s2, v7
	v_mad_u32_u24 v3, v3, s2, v7
	v_lshlrev_b32_e32 v7, 1, v2
	v_readlane_b32 s5, v253, 21
	v_and_b32_e32 v116, 56, v5
	v_and_b32_e32 v7, 32, v7
	v_and_b32_e32 v5, 24, v5
	s_mov_b32 s5, s3
	v_bfe_u32 v6, v2, 3, 3
	v_or_b32_e32 v9, 0xc0, v4
	v_lshlrev_b32_e32 v10, 4, v2
	v_add3_u32 v3, v3, v7, v5
	s_lshl_b64 s[6:7], s[4:5], 5
	v_bfe_u32 v147, v2, 4, 1
	v_and_b32_e32 v148, 15, v2
	s_mov_b32 s2, s4
	s_lshl_b64 s[22:23], s[4:5], 3
	v_or_b32_e32 v2, 0x1c0, v4
	v_readlane_b32 s8, v252, 14
	v_lshrrev_b32_e32 v9, 3, v9
	v_and_b32_e32 v10, 0x70, v10
	v_add_u32_e32 v139, 0x1200, v3
	v_add_u32_e32 v140, 0x1240, v3
	v_add_u32_e32 v141, 0x1b00, v3
	v_add_u32_e32 v142, 0x1b40, v3
	v_add_u32_e32 v143, 0x1680, v3
	v_add_u32_e32 v144, 0x16c0, v3
	v_add_u32_e32 v145, 0x1f80, v3
	v_add_u32_e32 v146, 0x1fc0, v3
	v_writelane_b32 v253, s2, 20
	v_min_u32_e32 v2, 0x1d0, v2
	v_readlane_b32 s9, v252, 15
	s_add_u32 s28, s8, s6
	v_sub_u32_e32 v3, v138, v1
	v_lshlrev_b32_e32 v118, 7, v6
	v_mov_b32_e32 v119, v191
	v_mov_b32_e32 v121, v191
	v_mov_b32_e32 v123, v191
	v_lshlrev_b32_e32 v124, 7, v9
	v_mov_b32_e32 v125, v191
	v_add_u32_e32 v115, s0, v10
	v_mul_u32_u24_e32 v117, 0x90, v6
	v_mul_u32_u24_e32 v135, 0x90, v9
	v_and_b32_e32 v126, 4, v6
	v_writelane_b32 v253, s3, 21
	v_lshl_add_u32 v149, v4, 2, s0
	v_cmp_gt_u32_e64 s[4:5], 17, v4
	s_addc_u32 s29, s9, s7
	v_add_u32_e32 v150, 27, v3
	s_add_i32 s21, s0, 0x27a0
	v_sub_u32_e32 v151, 0, v147
	v_sub_u32_e32 v152, v138, v148
	s_lshl_b32 s27, s1, 4
	v_lshlrev_b32_e32 v153, 2, v4
	v_lshlrev_b32_e32 v154, 2, v2
	s_branch .LBB0_2475
